# C (MLA) attention tile loop hand-rescheduled: QK(n+1) overlapped with softmax(n), PV(n) with rowmax(n+1); second Mneg copy removed
# speedup vs baseline: 1.0086x; 1.0086x over previous
.LBB0_206:
	v_readlane_b32 s18, v253, 41
	v_readlane_b32 s19, v253, 42
	s_and_b64 vcc, exec, s[18:19]
	s_cbranch_vccz .Lc_w03
	s_waitcnt vmcnt(2)
	s_branch .Lc_bar
.Lc_w03:
	s_waitcnt vmcnt(3)
.Lc_bar:
	s_barrier
	s_cmp_gt_u32 s20, 29
	s_cbranch_scc1 .Lc_nodma
	s_mul_i32 s0, s8, 0x5000
	v_add_u32_e32 v212, s0, v217
	v_add_u32_e32 v213, 0x2000, v212
	v_readfirstlane_b32 s0, v212
	s_mov_b32 m0, s0
	v_readfirstlane_b32 s0, v213
	global_load_lds_dwordx4 v[208:209], off
	s_mov_b32 m0, s0
	s_nop 0
	global_load_lds_dwordx4 v[204:205], off
	s_and_saveexec_b64 s[0:1], s[36:37]
	s_cbranch_execz .Lc_nokr
	v_add_u32_e32 v212, 0x4000, v212
	s_nop 0
	v_readfirstlane_b32 s18, v212
	s_mov_b32 m0, s18
	s_nop 0
	global_load_lds_dwordx4 v[206:207], off

.Lc_nodma:
	s_mul_i32 s0, s9, 0x5000
	v_add_u32_e32 v252, s0, v246
	v_add_u32_e32 v251, s0, v247
	v_add_u32_e32 v250, s0, v244
	v_add_u32_e32 v249, s0, v243
	v_add_u32_e32 v248, s0, v245
	v_add_u32_e32 v0, s0, v242
	ds_read_b128 v[194:197], v252
	ds_read_b128 v[198:201], v251
	ds_read_b128 v[190:193], v250
	ds_read_b128 v[186:189], v249
	ds_read_b128 v[182:185], v248 offset:16384
	ds_read_b128 v[166:169], v0 offset:16384
	s_waitcnt lgkmcnt(0)
	v_mfma_f32_32x32x16_bf16 v[98:113], v[194:197], v[138:141], v[82:97]
	v_mfma_f32_32x32x16_bf16 v[98:113], v[198:201], v[142:145], v[98:113]
	v_mfma_f32_32x32x16_bf16 v[98:113], v[190:193], v[150:153], v[98:113]
	v_mfma_f32_32x32x16_bf16 v[98:113], v[186:189], v[154:157], v[98:113]
	v_mfma_f32_32x32x16_bf16 v[98:113], v[182:185], v[146:149], v[98:113]
	v_mfma_f32_32x32x16_bf16 v[98:113], v[166:169], v[158:161], v[98:113]
	v_add_u32_e32 v213, s0, v241
	ds_read_b128 v[162:165], v213 offset:8192
	ds_read_b128 v[170:173], v213 offset:12288
	v_add_u32_e32 v213, s0, v240
	ds_read_b128 v[174:177], v213 offset:8192
	ds_read_b128 v[178:181], v213 offset:12288
	s_nop 5
	v_max_f32_e32 v212, v98, v99
	v_max3_f32 v212, v212, v100, v101
	v_max3_f32 v212, v212, v102, v103
	v_max3_f32 v212, v212, v104, v105
	v_max3_f32 v212, v212, v106, v107
	v_max3_f32 v212, v212, v108, v109
	v_max3_f32 v212, v212, v110, v111
	v_max3_f32 v212, v212, v112, v113
	v_mov_b32_e32 v213, v212
	s_nop 1
	v_permlane32_swap_b32_e32 v212, v213
	v_max_f32_e32 v212, v212, v213
	v_cmp_lt_f32_e32 vcc, s3, v212
	s_cbranch_vccnz .Lc_resc_b0
.Lc_resc_b0_ret:
	v_mfma_f32_32x32x16_bf16 v[66:81], v[194:197], v[114:117], v[82:97]
	v_exp_f32_e32 v98, v98
	v_exp_f32_e32 v99, v99
	v_exp_f32_e32 v100, v100
	v_exp_f32_e32 v101, v101
	v_add_f32_e32 v212, v99, v98
	v_mfma_f32_32x32x16_bf16 v[66:81], v[198:201], v[130:133], v[66:81]
	v_exp_f32_e32 v102, v102
	v_add_f32_e32 v212, v100, v212
	v_exp_f32_e32 v103, v103
	v_add_f32_e32 v212, v101, v212
	v_exp_f32_e32 v104, v104
	v_add_f32_e32 v212, v102, v212
	v_mfma_f32_32x32x16_bf16 v[66:81], v[190:193], v[126:129], v[66:81]
	v_exp_f32_e32 v105, v105
	v_add_f32_e32 v212, v103, v212
	v_cvt_pk_bf16_f32 v98, v98, v99
	v_exp_f32_e32 v106, v106
	v_add_f32_e32 v212, v104, v212
	v_cvt_pk_bf16_f32 v99, v100, v101
	v_mfma_f32_32x32x16_bf16 v[66:81], v[186:189], v[118:121], v[66:81]
	v_exp_f32_e32 v107, v107
	v_add_f32_e32 v212, v105, v212
	v_cvt_pk_bf16_f32 v100, v102, v103
	v_exp_f32_e32 v108, v108
	v_add_f32_e32 v212, v106, v212
	v_cvt_pk_bf16_f32 v101, v104, v105
	v_mfma_f32_32x32x16_bf16 v[66:81], v[182:185], v[122:125], v[66:81]
	v_exp_f32_e32 v109, v109
	v_add_f32_e32 v212, v107, v212
	v_exp_f32_e32 v110, v110
	v_add_f32_e32 v212, v108, v212
	v_exp_f32_e32 v111, v111
	v_add_f32_e32 v212, v109, v212
	v_mfma_f32_32x32x16_bf16 v[66:81], v[166:169], v[134:137], v[66:81]
	v_exp_f32_e32 v112, v112
	v_add_f32_e32 v212, v110, v212
	v_exp_f32_e32 v113, v113
	v_add_f32_e32 v212, v111, v212
	v_cvt_pk_bf16_f32 v102, v106, v107
	v_add_f32_e32 v212, v112, v212
	v_cvt_pk_bf16_f32 v103, v108, v109
	v_add_f32_e32 v212, v113, v212
	v_cvt_pk_bf16_f32 v104, v110, v111
	v_add_f32_e32 v203, v203, v212
	v_cvt_pk_bf16_f32 v105, v112, v113
	ds_read_b128 v[194:197], v252 offset:4096
	ds_read_b128 v[198:201], v251 offset:4096
	ds_read_b128 v[190:193], v250 offset:4096
	ds_read_b128 v[186:189], v249 offset:4096
	ds_read_b128 v[182:185], v248 offset:18432
	ds_read_b128 v[166:169], v0 offset:18432
	s_waitcnt lgkmcnt(6)
	v_mfma_f32_32x32x16_bf16 v[50:65], v[162:165], v[98:101], v[50:65]
	v_max_f32_e32 v212, v66, v67
	v_max3_f32 v212, v212, v68, v69
	v_mfma_f32_32x32x16_bf16 v[34:49], v[170:173], v[98:101], v[34:49]
	v_max3_f32 v212, v212, v70, v71
	v_max3_f32 v212, v212, v72, v73
	v_max3_f32 v212, v212, v74, v75
	v_mfma_f32_32x32x16_bf16 v[50:65], v[174:177], v[102:105], v[50:65]
	v_max3_f32 v212, v212, v76, v77
	v_max3_f32 v212, v212, v78, v79
	v_max3_f32 v212, v212, v80, v81
	v_mfma_f32_32x32x16_bf16 v[34:49], v[178:181], v[102:105], v[34:49]
	v_mov_b32_e32 v213, v212
	s_nop 1
	v_permlane32_swap_b32_e32 v212, v213
	v_max_f32_e32 v212, v212, v213
	v_cmp_lt_f32_e32 vcc, s3, v212
	s_cbranch_vccnz .Lc_resc_b1
.Lc_resc_b1_ret:
	s_waitcnt lgkmcnt(0)
	v_mfma_f32_32x32x16_bf16 v[98:113], v[194:197], v[138:141], v[82:97]
	v_exp_f32_e32 v66, v66
	v_exp_f32_e32 v67, v67
	v_exp_f32_e32 v68, v68
	v_exp_f32_e32 v69, v69
	v_add_f32_e32 v212, v67, v66
	v_mfma_f32_32x32x16_bf16 v[98:113], v[198:201], v[142:145], v[98:113]
	v_exp_f32_e32 v70, v70
	v_add_f32_e32 v212, v68, v212
	v_exp_f32_e32 v71, v71
	v_add_f32_e32 v212, v69, v212
	v_exp_f32_e32 v72, v72
	v_add_f32_e32 v212, v70, v212
	v_mfma_f32_32x32x16_bf16 v[98:113], v[190:193], v[150:153], v[98:113]
	v_exp_f32_e32 v73, v73
	v_add_f32_e32 v212, v71, v212
	v_cvt_pk_bf16_f32 v66, v66, v67
	v_exp_f32_e32 v74, v74
	v_add_f32_e32 v212, v72, v212
	v_cvt_pk_bf16_f32 v67, v68, v69
	v_mfma_f32_32x32x16_bf16 v[98:113], v[186:189], v[154:157], v[98:113]
	v_exp_f32_e32 v75, v75
	v_add_f32_e32 v212, v73, v212
	v_cvt_pk_bf16_f32 v68, v70, v71
	v_exp_f32_e32 v76, v76
	v_add_f32_e32 v212, v74, v212
	v_cvt_pk_bf16_f32 v69, v72, v73
	v_mfma_f32_32x32x16_bf16 v[98:113], v[182:185], v[146:149], v[98:113]
	v_exp_f32_e32 v77, v77
	v_add_f32_e32 v212, v75, v212
	v_exp_f32_e32 v78, v78
	v_add_f32_e32 v212, v76, v212
	v_exp_f32_e32 v79, v79
	v_add_f32_e32 v212, v77, v212
	v_mfma_f32_32x32x16_bf16 v[98:113], v[166:169], v[158:161], v[98:113]
	v_exp_f32_e32 v80, v80
	v_add_f32_e32 v212, v78, v212
	v_exp_f32_e32 v81, v81
	v_add_f32_e32 v212, v79, v212
	v_cvt_pk_bf16_f32 v70, v74, v75
	v_add_f32_e32 v212, v80, v212
	v_cvt_pk_bf16_f32 v71, v76, v77
	v_add_f32_e32 v212, v81, v212
	v_cvt_pk_bf16_f32 v72, v78, v79
	v_add_f32_e32 v202, v202, v212
	v_cvt_pk_bf16_f32 v73, v80, v81
	v_mfma_f32_32x32x16_bf16 v[18:33], v[162:165], v[66:69], v[18:33]
	v_max_f32_e32 v212, v98, v99
	v_max3_f32 v212, v212, v100, v101
	v_mfma_f32_32x32x16_bf16 v[2:17], v[170:173], v[66:69], v[2:17]
	v_max3_f32 v212, v212, v102, v103
	v_max3_f32 v212, v212, v104, v105
	v_max3_f32 v212, v212, v106, v107
	v_mfma_f32_32x32x16_bf16 v[18:33], v[174:177], v[70:73], v[18:33]
	v_max3_f32 v212, v212, v108, v109
	v_max3_f32 v212, v212, v110, v111
	v_max3_f32 v212, v212, v112, v113
	v_mfma_f32_32x32x16_bf16 v[2:17], v[178:181], v[70:73], v[2:17]
	v_add_u32_e32 v213, s0, v215
	ds_read_b128 v[162:165], v213 offset:8192
	ds_read_b128 v[170:173], v213 offset:12288
	v_add_u32_e32 v213, s0, v214
	ds_read_b128 v[174:177], v213 offset:8192
	ds_read_b128 v[178:181], v213 offset:12288
	v_mov_b32_e32 v213, v212
	s_nop 1
	v_permlane32_swap_b32_e32 v212, v213
	v_max_f32_e32 v212, v212, v213
	v_cmp_lt_f32_e32 vcc, s3, v212
	s_cbranch_vccnz .Lc_resc_b2
.Lc_resc_b2_ret:
	v_mfma_f32_32x32x16_bf16 v[66:81], v[194:197], v[114:117], v[82:97]
	v_exp_f32_e32 v98, v98
	v_exp_f32_e32 v99, v99
	v_exp_f32_e32 v100, v100
	v_exp_f32_e32 v101, v101
	v_add_f32_e32 v212, v99, v98
	v_mfma_f32_32x32x16_bf16 v[66:81], v[198:201], v[130:133], v[66:81]
	v_exp_f32_e32 v102, v102
	v_add_f32_e32 v212, v100, v212
	v_exp_f32_e32 v103, v103
	v_add_f32_e32 v212, v101, v212
	v_exp_f32_e32 v104, v104
	v_add_f32_e32 v212, v102, v212
	v_mfma_f32_32x32x16_bf16 v[66:81], v[190:193], v[126:129], v[66:81]
	v_exp_f32_e32 v105, v105
	v_add_f32_e32 v212, v103, v212
	v_cvt_pk_bf16_f32 v98, v98, v99
	v_exp_f32_e32 v106, v106
	v_add_f32_e32 v212, v104, v212
	v_cvt_pk_bf16_f32 v99, v100, v101
	v_mfma_f32_32x32x16_bf16 v[66:81], v[186:189], v[118:121], v[66:81]
	v_exp_f32_e32 v107, v107
	v_add_f32_e32 v212, v105, v212
	v_cvt_pk_bf16_f32 v100, v102, v103
	v_exp_f32_e32 v108, v108
	v_add_f32_e32 v212, v106, v212
	v_cvt_pk_bf16_f32 v101, v104, v105
	v_mfma_f32_32x32x16_bf16 v[66:81], v[182:185], v[122:125], v[66:81]
	v_exp_f32_e32 v109, v109
	v_add_f32_e32 v212, v107, v212
	v_exp_f32_e32 v110, v110
	v_add_f32_e32 v212, v108, v212
	v_exp_f32_e32 v111, v111
	v_add_f32_e32 v212, v109, v212
	v_mfma_f32_32x32x16_bf16 v[66:81], v[166:169], v[134:137], v[66:81]
	v_exp_f32_e32 v112, v112
	v_add_f32_e32 v212, v110, v212
	v_exp_f32_e32 v113, v113
	v_add_f32_e32 v212, v111, v212
	v_cvt_pk_bf16_f32 v102, v106, v107
	v_add_f32_e32 v212, v112, v212
	v_cvt_pk_bf16_f32 v103, v108, v109
	v_add_f32_e32 v212, v113, v212
	v_cvt_pk_bf16_f32 v104, v110, v111
	v_add_f32_e32 v203, v203, v212
	v_cvt_pk_bf16_f32 v105, v112, v113
	s_waitcnt lgkmcnt(0)
	v_mfma_f32_32x32x16_bf16 v[50:65], v[162:165], v[98:101], v[50:65]
	v_max_f32_e32 v212, v66, v67
	v_max3_f32 v212, v212, v68, v69
	v_mfma_f32_32x32x16_bf16 v[34:49], v[170:173], v[98:101], v[34:49]
	v_max3_f32 v212, v212, v70, v71
	v_max3_f32 v212, v212, v72, v73
	v_max3_f32 v212, v212, v74, v75
	v_mfma_f32_32x32x16_bf16 v[50:65], v[174:177], v[102:105], v[50:65]
	v_max3_f32 v212, v212, v76, v77
	v_max3_f32 v212, v212, v78, v79
	v_max3_f32 v212, v212, v80, v81
	v_mfma_f32_32x32x16_bf16 v[34:49], v[178:181], v[102:105], v[34:49]
	v_mov_b32_e32 v213, v212
	s_nop 1
	v_permlane32_swap_b32_e32 v212, v213
	v_max_f32_e32 v212, v212, v213
	v_cmp_lt_f32_e32 vcc, s3, v212
	s_cbranch_vccnz .Lc_resc_b3
.Lc_resc_b3_ret:
	v_exp_f32_e32 v66, v66
	v_exp_f32_e32 v67, v67
	v_exp_f32_e32 v68, v68
	v_exp_f32_e32 v69, v69
	v_add_f32_e32 v212, v67, v66
	v_exp_f32_e32 v70, v70
	v_add_f32_e32 v212, v68, v212
	v_exp_f32_e32 v71, v71
	v_add_f32_e32 v212, v69, v212
	v_exp_f32_e32 v72, v72
	v_add_f32_e32 v212, v70, v212
	v_exp_f32_e32 v73, v73
	v_add_f32_e32 v212, v71, v212
	v_cvt_pk_bf16_f32 v66, v66, v67
	v_exp_f32_e32 v74, v74
	v_add_f32_e32 v212, v72, v212
	v_cvt_pk_bf16_f32 v67, v68, v69
	v_exp_f32_e32 v75, v75
	v_add_f32_e32 v212, v73, v212
	v_cvt_pk_bf16_f32 v68, v70, v71
	v_exp_f32_e32 v76, v76
	v_add_f32_e32 v212, v74, v212
	v_cvt_pk_bf16_f32 v69, v72, v73
	v_exp_f32_e32 v77, v77
	v_add_f32_e32 v212, v75, v212
	v_exp_f32_e32 v78, v78
	v_add_f32_e32 v212, v76, v212
	v_exp_f32_e32 v79, v79
	v_add_f32_e32 v212, v77, v212
	v_exp_f32_e32 v80, v80
	v_add_f32_e32 v212, v78, v212
	v_exp_f32_e32 v81, v81
	v_add_f32_e32 v212, v79, v212
	v_cvt_pk_bf16_f32 v70, v74, v75
	v_add_f32_e32 v212, v80, v212
	v_cvt_pk_bf16_f32 v71, v76, v77
	v_add_f32_e32 v212, v81, v212
	v_cvt_pk_bf16_f32 v72, v78, v79
	v_add_f32_e32 v202, v202, v212
	v_cvt_pk_bf16_f32 v73, v80, v81
	v_mfma_f32_32x32x16_bf16 v[18:33], v[162:165], v[66:69], v[18:33]
	s_add_i32 s0, s9, 1
	s_cmp_lg_u32 s9, 2
	s_cselect_b32 s9, s0, 0
	v_mfma_f32_32x32x16_bf16 v[2:17], v[170:173], v[66:69], v[2:17]
	s_add_i32 s0, s8, 1
	s_add_i32 s20, s20, 1
	s_cmp_lg_u32 s8, 2
	s_cselect_b32 s8, s0, 0
	s_mov_b64 s[0:1], 0x53000
	v_lshl_add_u64 v[206:207], v[206:207], 0, s[0:1]
	v_mfma_f32_32x32x16_bf16 v[18:33], v[174:177], v[70:73], v[18:33]
	s_mov_b64 s[0:1], 0xa000
	v_lshl_add_u64 v[204:205], v[204:205], 0, s[26:27]
	v_lshl_add_u64 v[208:209], v[208:209], 0, s[0:1]
	v_mfma_f32_32x32x16_bf16 v[2:17], v[178:181], v[70:73], v[2:17]
	s_cmp_eq_u32 s20, 31
	s_cbranch_scc0 .LBB0_206
	v_mov_b64_e32 v[66:67], v[82:83]
	v_mov_b64_e32 v[68:69], v[84:85]
	v_mov_b64_e32 v[70:71], v[86:87]
	v_mov_b64_e32 v[72:73], v[88:89]
	v_mov_b64_e32 v[74:75], v[90:91]
	v_mov_b64_e32 v[76:77], v[92:93]
	v_mov_b64_e32 v[78:79], v[94:95]
	v_mov_b64_e32 v[80:81], v[96:97]
	s_branch .LBB0_223
.Lc_resc_b0:
	s_nop 15
	v_max_f32_e32 v213, 0, v212
	v_exp_f32_e64 v212, -v213
	v_add_f32_e32 v216, v216, v213
	v_sub_f32_e32 v98, v98, v213
	v_sub_f32_e32 v99, v99, v213
	v_sub_f32_e32 v100, v100, v213
	v_sub_f32_e32 v101, v101, v213
	v_sub_f32_e32 v102, v102, v213
	v_sub_f32_e32 v103, v103, v213
	v_sub_f32_e32 v104, v104, v213
	v_sub_f32_e32 v105, v105, v213
	v_sub_f32_e32 v106, v106, v213
	v_sub_f32_e32 v107, v107, v213
	v_sub_f32_e32 v108, v108, v213
	v_sub_f32_e32 v109, v109, v213
	v_sub_f32_e32 v110, v110, v213
	v_sub_f32_e32 v111, v111, v213
	v_sub_f32_e32 v112, v112, v213
	v_sub_f32_e32 v113, v113, v213
	v_mul_f32_e32 v50, v212, v50
	v_mul_f32_e32 v51, v212, v51
	v_mul_f32_e32 v52, v212, v52
	v_mul_f32_e32 v53, v212, v53
	v_mul_f32_e32 v54, v212, v54
	v_mul_f32_e32 v55, v212, v55
	v_mul_f32_e32 v56, v212, v56
	v_mul_f32_e32 v57, v212, v57
	v_mul_f32_e32 v58, v212, v58
	v_mul_f32_e32 v59, v212, v59
	v_mul_f32_e32 v60, v212, v60
	v_mul_f32_e32 v61, v212, v61
	v_mul_f32_e32 v62, v212, v62
	v_mul_f32_e32 v63, v212, v63
	v_mul_f32_e32 v64, v212, v64
	v_mul_f32_e32 v65, v212, v65
	v_mul_f32_e32 v34, v212, v34
	v_mul_f32_e32 v35, v212, v35
	v_mul_f32_e32 v36, v212, v36
	v_mul_f32_e32 v37, v212, v37
	v_mul_f32_e32 v38, v212, v38
	v_mul_f32_e32 v39, v212, v39
	v_mul_f32_e32 v40, v212, v40
	v_mul_f32_e32 v41, v212, v41
	v_mul_f32_e32 v42, v212, v42
	v_mul_f32_e32 v43, v212, v43
	v_mul_f32_e32 v44, v212, v44
	v_mul_f32_e32 v45, v212, v45
	v_mul_f32_e32 v46, v212, v46
	v_mul_f32_e32 v47, v212, v47
	v_mul_f32_e32 v48, v212, v48
	v_mul_f32_e32 v49, v212, v49
	v_mul_f32_e32 v18, v212, v18
	v_mul_f32_e32 v19, v212, v19
	v_mul_f32_e32 v20, v212, v20
	v_mul_f32_e32 v21, v212, v21
	v_mul_f32_e32 v22, v212, v22
	v_mul_f32_e32 v23, v212, v23
	v_mul_f32_e32 v24, v212, v24
	v_mul_f32_e32 v25, v212, v25
	v_mul_f32_e32 v26, v212, v26
	v_mul_f32_e32 v27, v212, v27
	v_mul_f32_e32 v28, v212, v28
	v_mul_f32_e32 v29, v212, v29
	v_mul_f32_e32 v30, v212, v30
	v_mul_f32_e32 v31, v212, v31
	v_mul_f32_e32 v32, v212, v32
	v_mul_f32_e32 v33, v212, v33
	v_mul_f32_e32 v2, v212, v2
	v_mul_f32_e32 v3, v212, v3
	v_mul_f32_e32 v4, v212, v4
	v_mul_f32_e32 v5, v212, v5
	v_mul_f32_e32 v6, v212, v6
	v_mul_f32_e32 v7, v212, v7
	v_mul_f32_e32 v8, v212, v8
	v_mul_f32_e32 v9, v212, v9
	v_mul_f32_e32 v10, v212, v10
	v_mul_f32_e32 v11, v212, v11
	v_mul_f32_e32 v12, v212, v12
	v_mul_f32_e32 v13, v212, v13
	v_mul_f32_e32 v14, v212, v14
	v_mul_f32_e32 v15, v212, v15
	v_mul_f32_e32 v16, v212, v16
	v_mul_f32_e32 v17, v212, v17
	v_mul_f32_e32 v202, v212, v202
	v_mul_f32_e32 v203, v212, v203
	v_xor_b32_e32 v82, 0x80000000, v216
	v_mov_b32_e32 v83, v82
	v_mov_b32_e32 v84, v82
	v_mov_b32_e32 v85, v82
	v_mov_b32_e32 v86, v82
	v_mov_b32_e32 v87, v82
	v_mov_b32_e32 v88, v82
	v_mov_b32_e32 v89, v82
	v_mov_b32_e32 v90, v82
	v_mov_b32_e32 v91, v82
	v_mov_b32_e32 v92, v82
	v_mov_b32_e32 v93, v82
	v_mov_b32_e32 v94, v82
	v_mov_b32_e32 v95, v82
	v_mov_b32_e32 v96, v82
	v_mov_b32_e32 v97, v82
	s_nop 1
	s_branch .Lc_resc_b0_ret
.Lc_resc_b1:
	s_nop 15
	v_max_f32_e32 v213, 0, v212
	v_exp_f32_e64 v212, -v213
	v_add_f32_e32 v216, v216, v213
	v_sub_f32_e32 v66, v66, v213
	v_sub_f32_e32 v67, v67, v213
	v_sub_f32_e32 v68, v68, v213
	v_sub_f32_e32 v69, v69, v213
	v_sub_f32_e32 v70, v70, v213
	v_sub_f32_e32 v71, v71, v213
	v_sub_f32_e32 v72, v72, v213
	v_sub_f32_e32 v73, v73, v213
	v_sub_f32_e32 v74, v74, v213
	v_sub_f32_e32 v75, v75, v213
	v_sub_f32_e32 v76, v76, v213
	v_sub_f32_e32 v77, v77, v213
	v_sub_f32_e32 v78, v78, v213
	v_sub_f32_e32 v79, v79, v213
	v_sub_f32_e32 v80, v80, v213
	v_sub_f32_e32 v81, v81, v213
	v_mul_f32_e32 v50, v212, v50
	v_mul_f32_e32 v51, v212, v51
	v_mul_f32_e32 v52, v212, v52
	v_mul_f32_e32 v53, v212, v53
	v_mul_f32_e32 v54, v212, v54
	v_mul_f32_e32 v55, v212, v55
	v_mul_f32_e32 v56, v212, v56
	v_mul_f32_e32 v57, v212, v57
	v_mul_f32_e32 v58, v212, v58
	v_mul_f32_e32 v59, v212, v59
	v_mul_f32_e32 v60, v212, v60
	v_mul_f32_e32 v61, v212, v61
	v_mul_f32_e32 v62, v212, v62
	v_mul_f32_e32 v63, v212, v63
	v_mul_f32_e32 v64, v212, v64
	v_mul_f32_e32 v65, v212, v65
	v_mul_f32_e32 v34, v212, v34
	v_mul_f32_e32 v35, v212, v35
	v_mul_f32_e32 v36, v212, v36
	v_mul_f32_e32 v37, v212, v37
	v_mul_f32_e32 v38, v212, v38
	v_mul_f32_e32 v39, v212, v39
	v_mul_f32_e32 v40, v212, v40
	v_mul_f32_e32 v41, v212, v41
	v_mul_f32_e32 v42, v212, v42
	v_mul_f32_e32 v43, v212, v43
	v_mul_f32_e32 v44, v212, v44
	v_mul_f32_e32 v45, v212, v45
	v_mul_f32_e32 v46, v212, v46
	v_mul_f32_e32 v47, v212, v47
	v_mul_f32_e32 v48, v212, v48
	v_mul_f32_e32 v49, v212, v49
	v_mul_f32_e32 v18, v212, v18
	v_mul_f32_e32 v19, v212, v19
	v_mul_f32_e32 v20, v212, v20
	v_mul_f32_e32 v21, v212, v21
	v_mul_f32_e32 v22, v212, v22
	v_mul_f32_e32 v23, v212, v23
	v_mul_f32_e32 v24, v212, v24
	v_mul_f32_e32 v25, v212, v25
	v_mul_f32_e32 v26, v212, v26
	v_mul_f32_e32 v27, v212, v27
	v_mul_f32_e32 v28, v212, v28
	v_mul_f32_e32 v29, v212, v29
	v_mul_f32_e32 v30, v212, v30
	v_mul_f32_e32 v31, v212, v31
	v_mul_f32_e32 v32, v212, v32
	v_mul_f32_e32 v33, v212, v33
	v_mul_f32_e32 v2, v212, v2
	v_mul_f32_e32 v3, v212, v3
	v_mul_f32_e32 v4, v212, v4
	v_mul_f32_e32 v5, v212, v5
	v_mul_f32_e32 v6, v212, v6
	v_mul_f32_e32 v7, v212, v7
	v_mul_f32_e32 v8, v212, v8
	v_mul_f32_e32 v9, v212, v9
	v_mul_f32_e32 v10, v212, v10
	v_mul_f32_e32 v11, v212, v11
	v_mul_f32_e32 v12, v212, v12
	v_mul_f32_e32 v13, v212, v13
	v_mul_f32_e32 v14, v212, v14
	v_mul_f32_e32 v15, v212, v15
	v_mul_f32_e32 v16, v212, v16
	v_mul_f32_e32 v17, v212, v17
	v_mul_f32_e32 v202, v212, v202
	v_mul_f32_e32 v203, v212, v203
	v_xor_b32_e32 v82, 0x80000000, v216
	v_mov_b32_e32 v83, v82
	v_mov_b32_e32 v84, v82
	v_mov_b32_e32 v85, v82
	v_mov_b32_e32 v86, v82
	v_mov_b32_e32 v87, v82
	v_mov_b32_e32 v88, v82
	v_mov_b32_e32 v89, v82
	v_mov_b32_e32 v90, v82
	v_mov_b32_e32 v91, v82
	v_mov_b32_e32 v92, v82
	v_mov_b32_e32 v93, v82
	v_mov_b32_e32 v94, v82
	v_mov_b32_e32 v95, v82
	v_mov_b32_e32 v96, v82
	v_mov_b32_e32 v97, v82
	s_nop 1
	s_branch .Lc_resc_b1_ret
